# FFN1-in mainloop: LDS-DMA loads issued before ds_reads in each load segment
# speedup vs baseline: 1.0038x; 1.0038x over previous
.LBB0_248:
	s_add_u32 s6, s54, 0xfffc0080
	s_addc_u32 s20, s55, -1
	s_add_i32 s21, 0, 0x10000
	s_cmp_eq_u32 s68, 12
	s_cselect_b32 s59, s33, s20
	s_cselect_b32 s58, s39, s6
	s_cselect_b32 s57, s45, s67
	s_cselect_b32 s56, s47, s66
	s_add_i32 s6, 0, 0x14000
	v_lshl_add_u64 v[202:203], s[54:55], 0, v[134:135]
	s_add_i32 m0, s60, 0xc000
	s_nop 0
	global_load_lds_dwordx4 v[202:203], off
	v_lshl_add_u64 v[202:203], s[54:55], 0, v[136:137]
	s_add_i32 m0, s60, 0xe000
	s_nop 0
	global_load_lds_dwordx4 v[202:203], off
	v_add_u32_e32 v48, s21, v173
	ds_read_b128 v[138:141], v48
	ds_read_b128 v[142:145], v48 offset:1024
	ds_read_b128 v[146:149], v48 offset:2048
	ds_read_b128 v[150:153], v48 offset:3072
	v_add_u32_e32 v48, s6, v173
	ds_read_b128 v[156:159], v48
	ds_read_b128 v[160:163], v48 offset:1024
	ds_read_b128 v[164:167], v48 offset:2048
	ds_read_b128 v[168:171], v48 offset:3072
	ds_read_b128 v[178:181], v176
	ds_read_b128 v[182:185], v176 offset:1024
	ds_read_b128 v[186:189], v176 offset:2048
	ds_read_b128 v[190:193], v176 offset:3072
	ds_read_b128 v[194:197], v176 offset:4096
	ds_read_b128 v[198:201], v176 offset:5120
	ds_read_b128 v[216:219], v176 offset:6144
	ds_read_b128 v[220:223], v176 offset:7168
	s_waitcnt vmcnt(8)
	s_waitcnt lgkmcnt(0)
	s_barrier
	s_setprio 1
	s_waitcnt lgkmcnt(0)
	v_mfma_f32_16x16x32_bf16 v[126:129], v[138:141], v[178:181], v[126:129]
	v_mfma_f32_16x16x32_bf16 v[122:125], v[146:149], v[178:181], v[122:125]
	v_mfma_f32_16x16x32_bf16 v[110:113], v[138:141], v[186:189], v[110:113]
	v_mfma_f32_16x16x32_bf16 v[106:109], v[146:149], v[186:189], v[106:109]
	v_mfma_f32_16x16x32_bf16 v[94:97], v[138:141], v[194:197], v[94:97]
	v_mfma_f32_16x16x32_bf16 v[90:93], v[146:149], v[194:197], v[90:93]
	v_mfma_f32_16x16x32_bf16 v[78:81], v[138:141], v[216:219], v[78:81]
	v_mfma_f32_16x16x32_bf16 v[74:77], v[146:149], v[216:219], v[74:77]
	v_mfma_f32_16x16x32_bf16 v[126:129], v[142:145], v[182:185], v[126:129]
	v_mfma_f32_16x16x32_bf16 v[122:125], v[150:153], v[182:185], v[122:125]
	v_mfma_f32_16x16x32_bf16 v[110:113], v[142:145], v[190:193], v[110:113]
	v_mfma_f32_16x16x32_bf16 v[106:109], v[150:153], v[190:193], v[106:109]
	v_mfma_f32_16x16x32_bf16 v[94:97], v[142:145], v[198:201], v[94:97]
	v_mfma_f32_16x16x32_bf16 v[90:93], v[150:153], v[198:201], v[90:93]
	v_mfma_f32_16x16x32_bf16 v[78:81], v[142:145], v[220:223], v[78:81]
	v_mfma_f32_16x16x32_bf16 v[74:77], v[150:153], v[220:223], v[74:77]
	s_setprio 0
	s_setprio 1
	v_mfma_f32_16x16x32_bf16 v[118:121], v[156:159], v[178:181], v[118:121]
	v_mfma_f32_16x16x32_bf16 v[114:117], v[164:167], v[178:181], v[114:117]
	v_mfma_f32_16x16x32_bf16 v[102:105], v[156:159], v[186:189], v[102:105]
	v_mfma_f32_16x16x32_bf16 v[98:101], v[164:167], v[186:189], v[98:101]
	v_mfma_f32_16x16x32_bf16 v[86:89], v[156:159], v[194:197], v[86:89]
	v_mfma_f32_16x16x32_bf16 v[82:85], v[164:167], v[194:197], v[82:85]
	v_mfma_f32_16x16x32_bf16 v[70:73], v[156:159], v[216:219], v[70:73]
	v_mfma_f32_16x16x32_bf16 v[66:69], v[164:167], v[216:219], v[66:69]
	v_mfma_f32_16x16x32_bf16 v[118:121], v[160:163], v[182:185], v[118:121]
	v_mfma_f32_16x16x32_bf16 v[114:117], v[168:171], v[182:185], v[114:117]
	v_mfma_f32_16x16x32_bf16 v[102:105], v[160:163], v[190:193], v[102:105]
	v_mfma_f32_16x16x32_bf16 v[98:101], v[168:171], v[190:193], v[98:101]
	v_mfma_f32_16x16x32_bf16 v[86:89], v[160:163], v[198:201], v[86:89]
	v_mfma_f32_16x16x32_bf16 v[82:85], v[168:171], v[198:201], v[82:85]
	v_mfma_f32_16x16x32_bf16 v[70:73], v[160:163], v[220:223], v[70:73]
	v_mfma_f32_16x16x32_bf16 v[66:69], v[168:171], v[220:223], v[66:69]
	s_setprio 0
	s_barrier
	s_add_i32 s20, s21, s9
	v_lshl_add_u64 v[202:203], s[56:57], 0, v[132:133]
	s_mov_b32 m0, s20
	s_nop 0
	global_load_lds_dwordx4 v[202:203], off
	s_add_i32 m0, s20, 0x2000
	s_add_u32 s20, s56, 0x40000
	v_lshl_add_u64 v[224:225], s[56:57], 0, v[130:131]
	s_addc_u32 s21, s57, 0
	s_add_i32 s6, s6, s9
	global_load_lds_dwordx4 v[224:225], off
	v_lshl_add_u64 v[226:227], s[20:21], 0, v[132:133]
	s_mov_b32 m0, s6
	v_lshl_add_u64 v[228:229], s[58:59], 0, v[130:131]
	global_load_lds_dwordx4 v[226:227], off
	v_lshl_add_u64 v[226:227], s[20:21], 0, v[130:131]
	s_add_i32 m0, s6, 0x2000
	s_nop 0
	global_load_lds_dwordx4 v[226:227], off
	v_lshl_add_u64 v[226:227], s[58:59], 0, v[132:133]
	s_mov_b32 m0, s60
	s_nop 0
	global_load_lds_dwordx4 v[226:227], off
	s_mov_b32 m0, s61
	s_nop 0
	global_load_lds_dwordx4 v[228:229], off
	ds_read_b128 v[178:181], v176 offset:16384
	ds_read_b128 v[182:185], v176 offset:17408
	ds_read_b128 v[186:189], v176 offset:18432
	ds_read_b128 v[190:193], v176 offset:19456
	ds_read_b128 v[194:197], v176 offset:20480
	ds_read_b128 v[198:201], v176 offset:21504
	ds_read_b128 v[216:219], v176 offset:22528
	ds_read_b128 v[220:223], v176 offset:23552
	s_waitcnt vmcnt(8)
	s_waitcnt lgkmcnt(0)
	s_barrier
	s_setprio 1
	s_waitcnt lgkmcnt(0)
	v_mfma_f32_16x16x32_bf16 v[62:65], v[138:141], v[178:181], v[62:65]
	v_mfma_f32_16x16x32_bf16 v[58:61], v[146:149], v[178:181], v[58:61]
	v_mfma_f32_16x16x32_bf16 v[44:47], v[138:141], v[186:189], v[44:47]
	v_mfma_f32_16x16x32_bf16 v[40:43], v[146:149], v[186:189], v[40:43]
	v_mfma_f32_16x16x32_bf16 v[28:31], v[138:141], v[194:197], v[28:31]
	v_mfma_f32_16x16x32_bf16 v[24:27], v[146:149], v[194:197], v[24:27]
	v_mfma_f32_16x16x32_bf16 v[12:15], v[138:141], v[216:219], v[12:15]
	v_mfma_f32_16x16x32_bf16 v[8:11], v[146:149], v[216:219], v[8:11]
	v_mfma_f32_16x16x32_bf16 v[62:65], v[142:145], v[182:185], v[62:65]
	v_mfma_f32_16x16x32_bf16 v[58:61], v[150:153], v[182:185], v[58:61]
	v_mfma_f32_16x16x32_bf16 v[44:47], v[142:145], v[190:193], v[44:47]
	v_mfma_f32_16x16x32_bf16 v[40:43], v[150:153], v[190:193], v[40:43]
	v_mfma_f32_16x16x32_bf16 v[28:31], v[142:145], v[198:201], v[28:31]
	v_mfma_f32_16x16x32_bf16 v[24:27], v[150:153], v[198:201], v[24:27]
	v_mfma_f32_16x16x32_bf16 v[12:15], v[142:145], v[220:223], v[12:15]
	v_mfma_f32_16x16x32_bf16 v[8:11], v[150:153], v[220:223], v[8:11]
	s_setprio 0
	s_setprio 1
	v_mfma_f32_16x16x32_bf16 v[54:57], v[156:159], v[178:181], v[54:57]
	v_mfma_f32_16x16x32_bf16 v[50:53], v[164:167], v[178:181], v[50:53]
	v_mfma_f32_16x16x32_bf16 v[36:39], v[156:159], v[186:189], v[36:39]
	v_mfma_f32_16x16x32_bf16 v[32:35], v[164:167], v[186:189], v[32:35]
	v_mfma_f32_16x16x32_bf16 v[20:23], v[156:159], v[194:197], v[20:23]
	v_mfma_f32_16x16x32_bf16 v[16:19], v[164:167], v[194:197], v[16:19]
	v_mfma_f32_16x16x32_bf16 v[4:7], v[156:159], v[216:219], v[4:7]
	v_mfma_f32_16x16x32_bf16 v[0:3], v[164:167], v[216:219], v[0:3]
	v_mfma_f32_16x16x32_bf16 v[54:57], v[160:163], v[182:185], v[54:57]
	v_mfma_f32_16x16x32_bf16 v[50:53], v[168:171], v[182:185], v[50:53]
	v_mfma_f32_16x16x32_bf16 v[36:39], v[160:163], v[190:193], v[36:39]
	v_mfma_f32_16x16x32_bf16 v[32:35], v[168:171], v[190:193], v[32:35]
	v_mfma_f32_16x16x32_bf16 v[20:23], v[160:163], v[198:201], v[20:23]
	v_mfma_f32_16x16x32_bf16 v[16:19], v[168:171], v[198:201], v[16:19]
	v_mfma_f32_16x16x32_bf16 v[4:7], v[160:163], v[220:223], v[4:7]
	v_mfma_f32_16x16x32_bf16 v[0:3], v[168:171], v[220:223], v[0:3]
	s_setprio 0
	s_barrier
	s_add_i32 s6, 0, 0x18000
	s_add_i32 s26, 0, 0x1c000
	s_add_u32 s20, s58, 0x40000
	s_addc_u32 s21, s59, 0
	s_mov_b32 m0, s62
	v_lshl_add_u64 v[230:231], s[20:21], 0, v[132:133]
	global_load_lds_dwordx4 v[230:231], off
	v_lshl_add_u64 v[230:231], s[20:21], 0, v[130:131]
	s_mov_b32 m0, s63
	s_nop 0
	global_load_lds_dwordx4 v[230:231], off
	v_add_u32_e32 v48, s6, v173
	ds_read_b128 v[138:141], v48
	ds_read_b128 v[142:145], v48 offset:1024
	ds_read_b128 v[146:149], v48 offset:2048
	ds_read_b128 v[150:153], v48 offset:3072
	v_add_u32_e32 v48, s26, v173
	ds_read_b128 v[156:159], v48
	ds_read_b128 v[160:163], v48 offset:1024
	ds_read_b128 v[164:167], v48 offset:2048
	ds_read_b128 v[168:171], v48 offset:3072
	ds_read_b128 v[178:181], v176 offset:32768
	ds_read_b128 v[182:185], v176 offset:33792
	ds_read_b128 v[186:189], v176 offset:34816
	ds_read_b128 v[190:193], v176 offset:35840
	ds_read_b128 v[194:197], v176 offset:36864
	ds_read_b128 v[198:201], v176 offset:37888
	ds_read_b128 v[216:219], v176 offset:38912
	ds_read_b128 v[220:223], v176 offset:39936
	s_waitcnt vmcnt(8)
	s_waitcnt lgkmcnt(0)
	s_barrier
	s_setprio 1
	s_waitcnt lgkmcnt(0)
	v_mfma_f32_16x16x32_bf16 v[126:129], v[138:141], v[178:181], v[126:129]
	v_mfma_f32_16x16x32_bf16 v[122:125], v[146:149], v[178:181], v[122:125]
	v_mfma_f32_16x16x32_bf16 v[110:113], v[138:141], v[186:189], v[110:113]
	v_mfma_f32_16x16x32_bf16 v[106:109], v[146:149], v[186:189], v[106:109]
	v_mfma_f32_16x16x32_bf16 v[94:97], v[138:141], v[194:197], v[94:97]
	v_mfma_f32_16x16x32_bf16 v[90:93], v[146:149], v[194:197], v[90:93]
	v_mfma_f32_16x16x32_bf16 v[78:81], v[138:141], v[216:219], v[78:81]
	v_mfma_f32_16x16x32_bf16 v[74:77], v[146:149], v[216:219], v[74:77]
	v_mfma_f32_16x16x32_bf16 v[126:129], v[142:145], v[182:185], v[126:129]
	v_mfma_f32_16x16x32_bf16 v[122:125], v[150:153], v[182:185], v[122:125]
	v_mfma_f32_16x16x32_bf16 v[110:113], v[142:145], v[190:193], v[110:113]
	v_mfma_f32_16x16x32_bf16 v[106:109], v[150:153], v[190:193], v[106:109]
	v_mfma_f32_16x16x32_bf16 v[94:97], v[142:145], v[198:201], v[94:97]
	v_mfma_f32_16x16x32_bf16 v[90:93], v[150:153], v[198:201], v[90:93]
	v_mfma_f32_16x16x32_bf16 v[78:81], v[142:145], v[220:223], v[78:81]
	v_mfma_f32_16x16x32_bf16 v[74:77], v[150:153], v[220:223], v[74:77]
	s_setprio 0
	s_setprio 1
	v_mfma_f32_16x16x32_bf16 v[118:121], v[156:159], v[178:181], v[118:121]
	v_mfma_f32_16x16x32_bf16 v[114:117], v[164:167], v[178:181], v[114:117]
	v_mfma_f32_16x16x32_bf16 v[102:105], v[156:159], v[186:189], v[102:105]
	v_mfma_f32_16x16x32_bf16 v[98:101], v[164:167], v[186:189], v[98:101]
	v_mfma_f32_16x16x32_bf16 v[86:89], v[156:159], v[194:197], v[86:89]
	v_mfma_f32_16x16x32_bf16 v[82:85], v[164:167], v[194:197], v[82:85]
	v_mfma_f32_16x16x32_bf16 v[70:73], v[156:159], v[216:219], v[70:73]
	v_mfma_f32_16x16x32_bf16 v[66:69], v[164:167], v[216:219], v[66:69]
	v_mfma_f32_16x16x32_bf16 v[118:121], v[160:163], v[182:185], v[118:121]
	v_mfma_f32_16x16x32_bf16 v[114:117], v[168:171], v[182:185], v[114:117]
	v_mfma_f32_16x16x32_bf16 v[102:105], v[160:163], v[190:193], v[102:105]
	v_mfma_f32_16x16x32_bf16 v[98:101], v[168:171], v[190:193], v[98:101]
	v_mfma_f32_16x16x32_bf16 v[86:89], v[160:163], v[198:201], v[86:89]
	v_mfma_f32_16x16x32_bf16 v[82:85], v[168:171], v[198:201], v[82:85]
	v_mfma_f32_16x16x32_bf16 v[70:73], v[160:163], v[220:223], v[70:73]
	v_mfma_f32_16x16x32_bf16 v[66:69], v[168:171], v[220:223], v[66:69]
	s_setprio 0
	s_barrier
	s_add_i32 s6, s6, s9
	v_lshl_add_u64 v[202:203], v[202:203], 0, s[30:31]
	s_mov_b32 m0, s6
	s_nop 0
	global_load_lds_dwordx4 v[202:203], off
	s_add_i32 m0, s6, 0x2000
	s_add_u32 s20, s56, 0x40080
	v_lshl_add_u64 v[202:203], v[224:225], 0, s[30:31]
	s_addc_u32 s21, s57, 0
	s_add_i32 s6, s26, s9
	global_load_lds_dwordx4 v[202:203], off
	v_lshl_add_u64 v[202:203], s[20:21], 0, v[132:133]
	s_mov_b32 m0, s6
	s_nop 0
	global_load_lds_dwordx4 v[202:203], off
	v_lshl_add_u64 v[202:203], s[20:21], 0, v[130:131]
	s_add_i32 m0, s6, 0x2000
	s_nop 0
	global_load_lds_dwordx4 v[202:203], off
	v_lshl_add_u64 v[202:203], v[226:227], 0, s[30:31]
	s_mov_b32 m0, s64
	s_nop 0
	global_load_lds_dwordx4 v[202:203], off
	v_lshl_add_u64 v[202:203], v[228:229], 0, s[30:31]
	s_mov_b32 m0, s65
	s_nop 0
	global_load_lds_dwordx4 v[202:203], off
	ds_read_b128 v[178:181], v176 offset:49152
	ds_read_b128 v[182:185], v176 offset:50176
	ds_read_b128 v[186:189], v176 offset:51200
	ds_read_b128 v[190:193], v176 offset:52224
	ds_read_b128 v[194:197], v176 offset:53248
	ds_read_b128 v[198:201], v176 offset:54272
	ds_read_b128 v[216:219], v176 offset:55296
	ds_read_b128 v[220:223], v176 offset:56320
	s_waitcnt vmcnt(8)
	s_waitcnt lgkmcnt(0)
	s_barrier
	s_setprio 1
	s_waitcnt lgkmcnt(0)
	v_mfma_f32_16x16x32_bf16 v[62:65], v[138:141], v[178:181], v[62:65]
	v_mfma_f32_16x16x32_bf16 v[58:61], v[146:149], v[178:181], v[58:61]
	v_mfma_f32_16x16x32_bf16 v[44:47], v[138:141], v[186:189], v[44:47]
	v_mfma_f32_16x16x32_bf16 v[40:43], v[146:149], v[186:189], v[40:43]
	v_mfma_f32_16x16x32_bf16 v[28:31], v[138:141], v[194:197], v[28:31]
	v_mfma_f32_16x16x32_bf16 v[24:27], v[146:149], v[194:197], v[24:27]
	v_mfma_f32_16x16x32_bf16 v[12:15], v[138:141], v[216:219], v[12:15]
	v_mfma_f32_16x16x32_bf16 v[8:11], v[146:149], v[216:219], v[8:11]
	v_mfma_f32_16x16x32_bf16 v[62:65], v[142:145], v[182:185], v[62:65]
	v_mfma_f32_16x16x32_bf16 v[58:61], v[150:153], v[182:185], v[58:61]
	v_mfma_f32_16x16x32_bf16 v[44:47], v[142:145], v[190:193], v[44:47]
	v_mfma_f32_16x16x32_bf16 v[40:43], v[150:153], v[190:193], v[40:43]
	v_mfma_f32_16x16x32_bf16 v[28:31], v[142:145], v[198:201], v[28:31]
	v_mfma_f32_16x16x32_bf16 v[24:27], v[150:153], v[198:201], v[24:27]
	v_mfma_f32_16x16x32_bf16 v[12:15], v[142:145], v[220:223], v[12:15]
	v_mfma_f32_16x16x32_bf16 v[8:11], v[150:153], v[220:223], v[8:11]
	s_setprio 0
	s_setprio 1
	v_mfma_f32_16x16x32_bf16 v[54:57], v[156:159], v[178:181], v[54:57]
	v_mfma_f32_16x16x32_bf16 v[50:53], v[164:167], v[178:181], v[50:53]
	v_mfma_f32_16x16x32_bf16 v[36:39], v[156:159], v[186:189], v[36:39]
	v_mfma_f32_16x16x32_bf16 v[32:35], v[164:167], v[186:189], v[32:35]
	v_mfma_f32_16x16x32_bf16 v[20:23], v[156:159], v[194:197], v[20:23]
	v_mfma_f32_16x16x32_bf16 v[16:19], v[164:167], v[194:197], v[16:19]
	v_mfma_f32_16x16x32_bf16 v[4:7], v[156:159], v[216:219], v[4:7]
	v_mfma_f32_16x16x32_bf16 v[0:3], v[164:167], v[216:219], v[0:3]
	v_mfma_f32_16x16x32_bf16 v[54:57], v[160:163], v[182:185], v[54:57]
	v_mfma_f32_16x16x32_bf16 v[50:53], v[168:171], v[182:185], v[50:53]
	v_mfma_f32_16x16x32_bf16 v[36:39], v[160:163], v[190:193], v[36:39]
	v_mfma_f32_16x16x32_bf16 v[32:35], v[168:171], v[190:193], v[32:35]
	v_mfma_f32_16x16x32_bf16 v[20:23], v[160:163], v[198:201], v[20:23]
	v_mfma_f32_16x16x32_bf16 v[16:19], v[168:171], v[198:201], v[16:19]
	v_mfma_f32_16x16x32_bf16 v[4:7], v[160:163], v[220:223], v[4:7]
	v_mfma_f32_16x16x32_bf16 v[0:3], v[168:171], v[220:223], v[0:3]
	s_setprio 0
	s_barrier
	s_add_i32 s68, s68, 2
	s_add_u32 s54, s54, 0x100
	s_addc_u32 s55, s55, 0
	s_add_u32 s66, s66, 0x100
	s_addc_u32 s67, s67, 0
	s_cmp_gt_u32 s68, 13
	s_cbranch_scc0 .LBB0_248
	s_and_b64 vcc, exec, s[42:43]
	s_cbranch_vccz .LBB0_251
	s_barrier
